# scan of the retention/hgrn jobs hand-written: scalar base + immediate offsets, no per-step constant refills or branches (about half the instructions per chunk)
# baseline (speedup 1.0000x reference)
; __device__ __forceinline__ float bf_lo(unsigned u) { return __uint_as_float(u << 16); }
; __device__ __forceinline__ float bf_hi(unsigned u) { return __uint_as_float(u & 0xffff0000u); }
; __device__ __forceinline__ unsigned pk2(float lo, float hi) { return pg8::cvt_pk_bf16(lo, hi); }
; #define SCAN_LOAD_D(slot, cc) { const int c_ = (cc) < NCH ? (cc) : NCH - 1; const bf16_t* bcn = bc0 + (size_t)c_ * 4096; \
;             _Pragma("unroll") for (int t = 0; t < 4; ++t) { cb[slot][t] = *(const u32x2*)(bcn + 256 * t); cm[slot][t] = mixer == 2 ? *(const f32x4*)(mv0 + (size_t)c_ * 64 + 16 * t) : (f32x4){g64, g64, g64, g64}; } }
; __device__ __forceinline__ void scan_phase(const Ctx& X, int wave, int lane) {
;     const int job = blockIdx.x;
;     if (job >= 192 || wave != 0) return;
;     asm volatile("" : "+v"(lane));
;     const int mixer = job >> 6, rem = job & 63, bh = rem >> 2, vg = rem & 3;
;     const int uid0 = (mixer * 16 + bh) * NCH;
;     const int r = lane & 15, q = lane >> 4;
;     bf16_t* bc0 = WSP(bf16_t, WS_BCS) + (size_t)uid0 * 4096 + (vg * 4 * 64 + lane) * 4;
;     float S[4][4];
; #pragma unroll
;     for (int t = 0; t < 4; ++t)
; #pragma unroll
;         for (int j = 0; j < 4; ++j) S[t][j] = 0.f;
;     ...
;         const int h = bh & 3;
;         const float g64 = __expf(64.0f * log1pf(-exp2f(-5.0f - (float)h)));
;         const float* mv0 = WSP(const float, WS_MVEC) + (size_t)(mixer == 2 ? uid0 - 2 * 2048 : 0) * 64 + 4 * q;
;         u32x2 cb[4][4]; f32x4 cm[4][4];
;     ...
;         SCAN_LOAD_D(0, 0) SCAN_LOAD_D(1, 1) SCAN_LOAD_D(2, 2)
; #pragma unroll 1
;         for (int c0 = 0; c0 < NCH; c0 += 4) {
; #pragma unroll
;             for (int k = 0; k < 4; ++k) {
;                 const int c = c0 + k;
;                 SCAN_LOAD_D((k + 3) & 3, c + 3)
;                 bf16_t* bcc = bc0 + (size_t)c * 4096;
; #pragma unroll
;                 for (int t = 0; t < 4; ++t) { u32x2 sp; sp.x = pk2(S[t][0], S[t][1]); sp.y = pk2(S[t][2], S[t][3]);
;                     asm volatile("" : "+v"(sp.x) : "v"(cb[k][t].x));
;                     *(u32x2*)(bcc + 256 * t) = sp;
;                     S[t][0] = cm[k][t].x * S[t][0] + bf_lo(cb[k][t].x); S[t][1] = cm[k][t].y * S[t][1] + bf_hi(cb[k][t].x);
;                     S[t][2] = cm[k][t].z * S[t][2] + bf_lo(cb[k][t].y); S[t][3] = cm[k][t].w * S[t][3] + bf_hi(cb[k][t].y); }
;             }
.Lgs1_pad:
.LBB0_675:
	s_or_b64 exec, exec, s[0:1]
	v_readlane_b32 s0, v253, 7
	v_readlane_b32 s1, v253, 8
	s_andn2_b64 vcc, exec, s[0:1]
	s_waitcnt lgkmcnt(0)
	s_barrier
	s_cbranch_vccnz .LBB0_739
	v_mov_b32_e32 v155, v232
	v_readlane_b32 s0, v253, 9
	v_readlane_b32 s4, v253, 14
	v_readlane_b32 s5, v253, 15
	v_add_lshl_u32 v86, v155, s0, 2
	v_readlane_b32 s0, v253, 12
	v_ashrrev_i32_e32 v87, 31, v86
	v_readlane_b32 s1, v253, 13
	s_and_b64 vcc, exec, s[4:5]
	s_nop 0
	v_lshl_add_u64 v[162:163], v[86:87], 1, s[0:1]
	s_mov_b64 s[0:1], -1
	s_cbranch_vccz .LBB0_736
	s_lshr_b32 s99, s2, 6
	s_and_b32 s20, s2, 63
	s_lshr_b32 s21, s20, 2
	s_and_b32 s20, s20, 3
	s_lshl_b32 s25, s99, 4
	s_add_i32 s25, s25, s21
	s_lshl_b32 s25, s25, 20
	s_lshl_b32 s20, s20, 11
	s_add_u32 s44, s30, 0x3500000
	s_addc_u32 s45, s31, 0
	s_add_u32 s44, s44, s25
	s_addc_u32 s45, s45, 0
	s_add_u32 s44, s44, s20
	s_addc_u32 s45, s45, 0
	s_lshl_b32 s21, s21, 15
	s_add_u32 s46, s30, 0x1f600000
	s_addc_u32 s47, s31, 0
	s_add_u32 s46, s46, s21
	s_addc_u32 s47, s47, 0
	v_lshlrev_b32_e32 v6, 3, v155
	v_lshrrev_b32_e32 v7, 4, v155
	v_lshlrev_b32_e32 v7, 4, v7
	v_mov_b32_e32 v8, 0
	v_mov_b32_e32 v9, 0
	v_mov_b32_e32 v10, 0
	v_mov_b32_e32 v11, 0
	v_mov_b32_e32 v12, 0
	v_mov_b32_e32 v13, 0
	v_mov_b32_e32 v14, 0
	v_mov_b32_e32 v15, 0
	v_mov_b32_e32 v16, 0
	v_mov_b32_e32 v17, 0
	v_mov_b32_e32 v18, 0
	v_mov_b32_e32 v19, 0
	v_mov_b32_e32 v20, 0
	v_mov_b32_e32 v21, 0
	v_mov_b32_e32 v22, 0
	v_mov_b32_e32 v23, 0
	s_cmp_eq_u32 s99, 2
	s_cbranch_scc1 .Lsd2_start
.Lsd0_start:
	s_mov_b32 s39, 0
	s_add_i32 s37, s39, 0
	s_min_u32 s37, s37, 0x7f
	s_lshl_b32 s38, s37, 13
	s_add_u32 s82, s44, s38
	s_addc_u32 s83, s45, 0
	global_load_dwordx2 v[24:25], v6, s[82:83]
	global_load_dwordx2 v[26:27], v6, s[82:83] offset:512
	global_load_dwordx2 v[28:29], v6, s[82:83] offset:1024
	global_load_dwordx2 v[30:31], v6, s[82:83] offset:1536
	s_add_i32 s37, s39, 1
	s_min_u32 s37, s37, 0x7f
	s_lshl_b32 s38, s37, 13
	s_add_u32 s82, s44, s38
	s_addc_u32 s83, s45, 0
	global_load_dwordx2 v[32:33], v6, s[82:83]
	global_load_dwordx2 v[34:35], v6, s[82:83] offset:512
	global_load_dwordx2 v[36:37], v6, s[82:83] offset:1024
	global_load_dwordx2 v[38:39], v6, s[82:83] offset:1536
	s_add_i32 s37, s39, 2
	s_min_u32 s37, s37, 0x7f
	s_lshl_b32 s38, s37, 13
	s_add_u32 s82, s44, s38
	s_addc_u32 s83, s45, 0
	global_load_dwordx2 v[40:41], v6, s[82:83]
	global_load_dwordx2 v[42:43], v6, s[82:83] offset:512
	global_load_dwordx2 v[44:45], v6, s[82:83] offset:1024
	global_load_dwordx2 v[46:47], v6, s[82:83] offset:1536
	s_waitcnt vmcnt(0)
.Lsd0_loop:
	s_add_i32 s37, s39, 3
	s_min_u32 s37, s37, 0x7f
	s_lshl_b32 s38, s37, 13
	s_add_u32 s82, s44, s38
	s_addc_u32 s83, s45, 0
	global_load_dwordx2 v[48:49], v6, s[82:83]
	global_load_dwordx2 v[50:51], v6, s[82:83] offset:512
	global_load_dwordx2 v[52:53], v6, s[82:83] offset:1024
	global_load_dwordx2 v[54:55], v6, s[82:83] offset:1536
	s_waitcnt vmcnt(24)
	v_cvt_pk_bf16_f32 v120, v8, v9
	v_cvt_pk_bf16_f32 v121, v10, v11
	v_cvt_pk_bf16_f32 v122, v12, v13
	v_cvt_pk_bf16_f32 v123, v14, v15
	v_cvt_pk_bf16_f32 v124, v16, v17
	v_cvt_pk_bf16_f32 v125, v18, v19
	v_cvt_pk_bf16_f32 v126, v20, v21
	v_cvt_pk_bf16_f32 v127, v22, v23
	s_add_i32 s37, s39, 0
	s_lshl_b32 s38, s37, 13
	s_add_u32 s40, s44, s38
	s_addc_u32 s41, s45, 0
	global_store_dwordx2 v6, v[120:121], s[40:41]
	global_store_dwordx2 v6, v[122:123], s[40:41] offset:512
	global_store_dwordx2 v6, v[124:125], s[40:41] offset:1024
	global_store_dwordx2 v6, v[126:127], s[40:41] offset:1536
	v_lshlrev_b32_e32 v128, 16, v24
	v_and_b32_e32 v129, 0xffff0000, v24
	v_lshlrev_b32_e32 v130, 16, v25
	v_and_b32_e32 v131, 0xffff0000, v25
	v_fma_f32 v8, v0, v8, v128
	v_fma_f32 v9, v0, v9, v129
	v_fma_f32 v10, v0, v10, v130
	v_fma_f32 v11, v0, v11, v131
	v_lshlrev_b32_e32 v128, 16, v26
	v_and_b32_e32 v129, 0xffff0000, v26
	v_lshlrev_b32_e32 v130, 16, v27
	v_and_b32_e32 v131, 0xffff0000, v27
	v_fma_f32 v12, v0, v12, v128
	v_fma_f32 v13, v0, v13, v129
	v_fma_f32 v14, v0, v14, v130
	v_fma_f32 v15, v0, v15, v131
	v_lshlrev_b32_e32 v128, 16, v28
	v_and_b32_e32 v129, 0xffff0000, v28
	v_lshlrev_b32_e32 v130, 16, v29
	v_and_b32_e32 v131, 0xffff0000, v29
	v_fma_f32 v16, v0, v16, v128
	v_fma_f32 v17, v0, v17, v129
	v_fma_f32 v18, v0, v18, v130
	v_fma_f32 v19, v0, v19, v131
	v_lshlrev_b32_e32 v128, 16, v30
	v_and_b32_e32 v129, 0xffff0000, v30
	v_lshlrev_b32_e32 v130, 16, v31
	v_and_b32_e32 v131, 0xffff0000, v31
	v_fma_f32 v20, v0, v20, v128
	v_fma_f32 v21, v0, v21, v129
	v_fma_f32 v22, v0, v22, v130
	v_fma_f32 v23, v0, v23, v131
	s_add_i32 s37, s39, 4
	s_min_u32 s37, s37, 0x7f
	s_lshl_b32 s38, s37, 13
	s_add_u32 s82, s44, s38
	s_addc_u32 s83, s45, 0
	global_load_dwordx2 v[24:25], v6, s[82:83]
	global_load_dwordx2 v[26:27], v6, s[82:83] offset:512
	global_load_dwordx2 v[28:29], v6, s[82:83] offset:1024
	global_load_dwordx2 v[30:31], v6, s[82:83] offset:1536
	s_waitcnt vmcnt(24)
; __device__ __forceinline__ float bf_lo(unsigned u) { return __uint_as_float(u << 16); }
; __device__ __forceinline__ float bf_hi(unsigned u) { return __uint_as_float(u & 0xffff0000u); }
; __device__ __forceinline__ unsigned pk2(float lo, float hi) { return pg8::cvt_pk_bf16(lo, hi); }
; #define SCAN_LOAD_D(slot, cc) { const int c_ = (cc) < NCH ? (cc) : NCH - 1; const bf16_t* bcn = bc0 + (size_t)c_ * 4096; \
;             _Pragma("unroll") for (int t = 0; t < 4; ++t) { cb[slot][t] = *(const u32x2*)(bcn + 256 * t); cm[slot][t] = mixer == 2 ? *(const f32x4*)(mv0 + (size_t)c_ * 64 + 16 * t) : (f32x4){g64, g64, g64, g64}; } }
; __device__ __forceinline__ void scan_phase(const Ctx& X, int wave, int lane) {
;     ...
;         for (int c0 = 0; c0 < NCH; c0 += 4) {
; #pragma unroll
;             for (int k = 0; k < 4; ++k) {
;                 const int c = c0 + k;
;                 SCAN_LOAD_D((k + 3) & 3, c + 3)
;                 bf16_t* bcc = bc0 + (size_t)c * 4096;
; #pragma unroll
;                 for (int t = 0; t < 4; ++t) { u32x2 sp; sp.x = pk2(S[t][0], S[t][1]); sp.y = pk2(S[t][2], S[t][3]);
;                     asm volatile("" : "+v"(sp.x) : "v"(cb[k][t].x));
;                     *(u32x2*)(bcc + 256 * t) = sp;
;                     S[t][0] = cm[k][t].x * S[t][0] + bf_lo(cb[k][t].x); S[t][1] = cm[k][t].y * S[t][1] + bf_hi(cb[k][t].x);
;                     S[t][2] = cm[k][t].z * S[t][2] + bf_lo(cb[k][t].y); S[t][3] = cm[k][t].w * S[t][3] + bf_hi(cb[k][t].y); }
;             }
	v_cvt_pk_bf16_f32 v120, v8, v9
	v_cvt_pk_bf16_f32 v121, v10, v11
	v_cvt_pk_bf16_f32 v122, v12, v13
	v_cvt_pk_bf16_f32 v123, v14, v15
	v_cvt_pk_bf16_f32 v124, v16, v17
	v_cvt_pk_bf16_f32 v125, v18, v19
	v_cvt_pk_bf16_f32 v126, v20, v21
	v_cvt_pk_bf16_f32 v127, v22, v23
	s_add_i32 s37, s39, 1
	s_lshl_b32 s38, s37, 13
	s_add_u32 s40, s44, s38
	s_addc_u32 s41, s45, 0
	global_store_dwordx2 v6, v[120:121], s[40:41]
	global_store_dwordx2 v6, v[122:123], s[40:41] offset:512
	global_store_dwordx2 v6, v[124:125], s[40:41] offset:1024
	global_store_dwordx2 v6, v[126:127], s[40:41] offset:1536
	v_lshlrev_b32_e32 v128, 16, v32
	v_and_b32_e32 v129, 0xffff0000, v32
	v_lshlrev_b32_e32 v130, 16, v33
	v_and_b32_e32 v131, 0xffff0000, v33
	v_fma_f32 v8, v0, v8, v128
	v_fma_f32 v9, v0, v9, v129
	v_fma_f32 v10, v0, v10, v130
	v_fma_f32 v11, v0, v11, v131
	v_lshlrev_b32_e32 v128, 16, v34
	v_and_b32_e32 v129, 0xffff0000, v34
	v_lshlrev_b32_e32 v130, 16, v35
	v_and_b32_e32 v131, 0xffff0000, v35
	v_fma_f32 v12, v0, v12, v128
	v_fma_f32 v13, v0, v13, v129
	v_fma_f32 v14, v0, v14, v130
	v_fma_f32 v15, v0, v15, v131
	v_lshlrev_b32_e32 v128, 16, v36
	v_and_b32_e32 v129, 0xffff0000, v36
	v_lshlrev_b32_e32 v130, 16, v37
	v_and_b32_e32 v131, 0xffff0000, v37
	v_fma_f32 v16, v0, v16, v128
	v_fma_f32 v17, v0, v17, v129
	v_fma_f32 v18, v0, v18, v130
	v_fma_f32 v19, v0, v19, v131
	v_lshlrev_b32_e32 v128, 16, v38
	v_and_b32_e32 v129, 0xffff0000, v38
	v_lshlrev_b32_e32 v130, 16, v39
	v_and_b32_e32 v131, 0xffff0000, v39
	v_fma_f32 v20, v0, v20, v128
	v_fma_f32 v21, v0, v21, v129
	v_fma_f32 v22, v0, v22, v130
	v_fma_f32 v23, v0, v23, v131
	s_add_i32 s37, s39, 5
	s_min_u32 s37, s37, 0x7f
	s_lshl_b32 s38, s37, 13
	s_add_u32 s82, s44, s38
	s_addc_u32 s83, s45, 0
	global_load_dwordx2 v[32:33], v6, s[82:83]
	global_load_dwordx2 v[34:35], v6, s[82:83] offset:512
	global_load_dwordx2 v[36:37], v6, s[82:83] offset:1024
	global_load_dwordx2 v[38:39], v6, s[82:83] offset:1536
	s_waitcnt vmcnt(24)
	v_cvt_pk_bf16_f32 v120, v8, v9
	v_cvt_pk_bf16_f32 v121, v10, v11
	v_cvt_pk_bf16_f32 v122, v12, v13
	v_cvt_pk_bf16_f32 v123, v14, v15
	v_cvt_pk_bf16_f32 v124, v16, v17
	v_cvt_pk_bf16_f32 v125, v18, v19
	v_cvt_pk_bf16_f32 v126, v20, v21
	v_cvt_pk_bf16_f32 v127, v22, v23
	s_add_i32 s37, s39, 2
	s_lshl_b32 s38, s37, 13
	s_add_u32 s40, s44, s38
	s_addc_u32 s41, s45, 0
	global_store_dwordx2 v6, v[120:121], s[40:41]
	global_store_dwordx2 v6, v[122:123], s[40:41] offset:512
	global_store_dwordx2 v6, v[124:125], s[40:41] offset:1024
	global_store_dwordx2 v6, v[126:127], s[40:41] offset:1536
	v_lshlrev_b32_e32 v128, 16, v40
	v_and_b32_e32 v129, 0xffff0000, v40
	v_lshlrev_b32_e32 v130, 16, v41
	v_and_b32_e32 v131, 0xffff0000, v41
	v_fma_f32 v8, v0, v8, v128
	v_fma_f32 v9, v0, v9, v129
	v_fma_f32 v10, v0, v10, v130
	v_fma_f32 v11, v0, v11, v131
	v_lshlrev_b32_e32 v128, 16, v42
	v_and_b32_e32 v129, 0xffff0000, v42
	v_lshlrev_b32_e32 v130, 16, v43
	v_and_b32_e32 v131, 0xffff0000, v43
	v_fma_f32 v12, v0, v12, v128
	v_fma_f32 v13, v0, v13, v129
	v_fma_f32 v14, v0, v14, v130
	v_fma_f32 v15, v0, v15, v131
	v_lshlrev_b32_e32 v128, 16, v44
	v_and_b32_e32 v129, 0xffff0000, v44
	v_lshlrev_b32_e32 v130, 16, v45
	v_and_b32_e32 v131, 0xffff0000, v45
	v_fma_f32 v16, v0, v16, v128
	v_fma_f32 v17, v0, v17, v129
	v_fma_f32 v18, v0, v18, v130
	v_fma_f32 v19, v0, v19, v131
	v_lshlrev_b32_e32 v128, 16, v46
	v_and_b32_e32 v129, 0xffff0000, v46
	v_lshlrev_b32_e32 v130, 16, v47
	v_and_b32_e32 v131, 0xffff0000, v47
	v_fma_f32 v20, v0, v20, v128
	v_fma_f32 v21, v0, v21, v129
	v_fma_f32 v22, v0, v22, v130
	v_fma_f32 v23, v0, v23, v131
	s_add_i32 s37, s39, 6
	s_min_u32 s37, s37, 0x7f
	s_lshl_b32 s38, s37, 13
	s_add_u32 s82, s44, s38
	s_addc_u32 s83, s45, 0
	global_load_dwordx2 v[40:41], v6, s[82:83]
	global_load_dwordx2 v[42:43], v6, s[82:83] offset:512
	global_load_dwordx2 v[44:45], v6, s[82:83] offset:1024
	global_load_dwordx2 v[46:47], v6, s[82:83] offset:1536
	s_waitcnt vmcnt(24)
	v_cvt_pk_bf16_f32 v120, v8, v9
	v_cvt_pk_bf16_f32 v121, v10, v11
	v_cvt_pk_bf16_f32 v122, v12, v13
	v_cvt_pk_bf16_f32 v123, v14, v15
	v_cvt_pk_bf16_f32 v124, v16, v17
	v_cvt_pk_bf16_f32 v125, v18, v19
	v_cvt_pk_bf16_f32 v126, v20, v21
	v_cvt_pk_bf16_f32 v127, v22, v23
	s_add_i32 s37, s39, 3
	s_lshl_b32 s38, s37, 13
	s_add_u32 s40, s44, s38
	s_addc_u32 s41, s45, 0
	global_store_dwordx2 v6, v[120:121], s[40:41]
	global_store_dwordx2 v6, v[122:123], s[40:41] offset:512
	global_store_dwordx2 v6, v[124:125], s[40:41] offset:1024
	global_store_dwordx2 v6, v[126:127], s[40:41] offset:1536
	v_lshlrev_b32_e32 v128, 16, v48
	v_and_b32_e32 v129, 0xffff0000, v48
	v_lshlrev_b32_e32 v130, 16, v49
	v_and_b32_e32 v131, 0xffff0000, v49
	v_fma_f32 v8, v0, v8, v128
	v_fma_f32 v9, v0, v9, v129
	v_fma_f32 v10, v0, v10, v130
	v_fma_f32 v11, v0, v11, v131
	v_lshlrev_b32_e32 v128, 16, v50
	v_and_b32_e32 v129, 0xffff0000, v50
	v_lshlrev_b32_e32 v130, 16, v51
	v_and_b32_e32 v131, 0xffff0000, v51
	v_fma_f32 v12, v0, v12, v128
	v_fma_f32 v13, v0, v13, v129
	v_fma_f32 v14, v0, v14, v130
	v_fma_f32 v15, v0, v15, v131
	v_lshlrev_b32_e32 v128, 16, v52
	v_and_b32_e32 v129, 0xffff0000, v52
	v_lshlrev_b32_e32 v130, 16, v53
	v_and_b32_e32 v131, 0xffff0000, v53
	v_fma_f32 v16, v0, v16, v128
	v_fma_f32 v17, v0, v17, v129
	v_fma_f32 v18, v0, v18, v130
	v_fma_f32 v19, v0, v19, v131
	v_lshlrev_b32_e32 v128, 16, v54
	v_and_b32_e32 v129, 0xffff0000, v54
	v_lshlrev_b32_e32 v130, 16, v55
	v_and_b32_e32 v131, 0xffff0000, v55
	v_fma_f32 v20, v0, v20, v128
	v_fma_f32 v21, v0, v21, v129
	v_fma_f32 v22, v0, v22, v130
	v_fma_f32 v23, v0, v23, v131
	s_add_i32 s39, s39, 4
	s_cmpk_lt_u32 s39, 0x80
	s_cbranch_scc1 .Lsd0_loop
	s_branch .LBB0_739
; __device__ __forceinline__ float bf_lo(unsigned u) { return __uint_as_float(u << 16); }
; __device__ __forceinline__ float bf_hi(unsigned u) { return __uint_as_float(u & 0xffff0000u); }
; __device__ __forceinline__ unsigned pk2(float lo, float hi) { return pg8::cvt_pk_bf16(lo, hi); }
; #define SCAN_LOAD_D(slot, cc) { const int c_ = (cc) < NCH ? (cc) : NCH - 1; const bf16_t* bcn = bc0 + (size_t)c_ * 4096; \
;             _Pragma("unroll") for (int t = 0; t < 4; ++t) { cb[slot][t] = *(const u32x2*)(bcn + 256 * t); cm[slot][t] = mixer == 2 ? *(const f32x4*)(mv0 + (size_t)c_ * 64 + 16 * t) : (f32x4){g64, g64, g64, g64}; } }
; __device__ __forceinline__ void scan_phase(const Ctx& X, int wave, int lane) {
;     ...
;         SCAN_LOAD_D(0, 0) SCAN_LOAD_D(1, 1) SCAN_LOAD_D(2, 2)
; #pragma unroll 1
;         for (int c0 = 0; c0 < NCH; c0 += 4) {
; #pragma unroll
;             for (int k = 0; k < 4; ++k) {
;                 const int c = c0 + k;
;                 SCAN_LOAD_D((k + 3) & 3, c + 3)
;                 bf16_t* bcc = bc0 + (size_t)c * 4096;
; #pragma unroll
;                 for (int t = 0; t < 4; ++t) { u32x2 sp; sp.x = pk2(S[t][0], S[t][1]); sp.y = pk2(S[t][2], S[t][3]);
;                     asm volatile("" : "+v"(sp.x) : "v"(cb[k][t].x));
;                     *(u32x2*)(bcc + 256 * t) = sp;
;                     S[t][0] = cm[k][t].x * S[t][0] + bf_lo(cb[k][t].x); S[t][1] = cm[k][t].y * S[t][1] + bf_hi(cb[k][t].x);
;                     S[t][2] = cm[k][t].z * S[t][2] + bf_lo(cb[k][t].y); S[t][3] = cm[k][t].w * S[t][3] + bf_hi(cb[k][t].y); }
;             }
.Lsd2_start:
	s_mov_b32 s39, 0
	s_add_i32 s37, s39, 0
	s_min_u32 s37, s37, 0x7f
	s_lshl_b32 s38, s37, 13
	s_add_u32 s82, s44, s38
	s_addc_u32 s83, s45, 0
	global_load_dwordx2 v[24:25], v6, s[82:83]
	global_load_dwordx2 v[26:27], v6, s[82:83] offset:512
	global_load_dwordx2 v[28:29], v6, s[82:83] offset:1024
	global_load_dwordx2 v[30:31], v6, s[82:83] offset:1536
	s_lshl_b32 s38, s37, 8
	s_add_u32 s82, s46, s38
	s_addc_u32 s83, s47, 0
	global_load_dwordx4 v[56:59], v7, s[82:83]
	global_load_dwordx4 v[60:63], v7, s[82:83] offset:64
	global_load_dwordx4 v[64:67], v7, s[82:83] offset:128
	global_load_dwordx4 v[68:71], v7, s[82:83] offset:192
	s_add_i32 s37, s39, 1
	s_min_u32 s37, s37, 0x7f
	s_lshl_b32 s38, s37, 13
	s_add_u32 s82, s44, s38
	s_addc_u32 s83, s45, 0
	global_load_dwordx2 v[32:33], v6, s[82:83]
	global_load_dwordx2 v[34:35], v6, s[82:83] offset:512
	global_load_dwordx2 v[36:37], v6, s[82:83] offset:1024
	global_load_dwordx2 v[38:39], v6, s[82:83] offset:1536
	s_lshl_b32 s38, s37, 8
	s_add_u32 s82, s46, s38
	s_addc_u32 s83, s47, 0
	global_load_dwordx4 v[72:75], v7, s[82:83]
	global_load_dwordx4 v[76:79], v7, s[82:83] offset:64
	global_load_dwordx4 v[80:83], v7, s[82:83] offset:128
	global_load_dwordx4 v[84:87], v7, s[82:83] offset:192
	s_add_i32 s37, s39, 2
	s_min_u32 s37, s37, 0x7f
	s_lshl_b32 s38, s37, 13
	s_add_u32 s82, s44, s38
	s_addc_u32 s83, s45, 0
	global_load_dwordx2 v[40:41], v6, s[82:83]
	global_load_dwordx2 v[42:43], v6, s[82:83] offset:512
	global_load_dwordx2 v[44:45], v6, s[82:83] offset:1024
	global_load_dwordx2 v[46:47], v6, s[82:83] offset:1536
	s_lshl_b32 s38, s37, 8
	s_add_u32 s82, s46, s38
	s_addc_u32 s83, s47, 0
	global_load_dwordx4 v[88:91], v7, s[82:83]
	global_load_dwordx4 v[92:95], v7, s[82:83] offset:64
	global_load_dwordx4 v[96:99], v7, s[82:83] offset:128
	global_load_dwordx4 v[100:103], v7, s[82:83] offset:192
	s_waitcnt vmcnt(0)
.Lsd2_loop:
	s_add_i32 s37, s39, 3
	s_min_u32 s37, s37, 0x7f
	s_lshl_b32 s38, s37, 13
	s_add_u32 s82, s44, s38
	s_addc_u32 s83, s45, 0
	global_load_dwordx2 v[48:49], v6, s[82:83]
	global_load_dwordx2 v[50:51], v6, s[82:83] offset:512
	global_load_dwordx2 v[52:53], v6, s[82:83] offset:1024
	global_load_dwordx2 v[54:55], v6, s[82:83] offset:1536
	s_lshl_b32 s38, s37, 8
	s_add_u32 s82, s46, s38
	s_addc_u32 s83, s47, 0
	global_load_dwordx4 v[104:107], v7, s[82:83]
	global_load_dwordx4 v[108:111], v7, s[82:83] offset:64
	global_load_dwordx4 v[112:115], v7, s[82:83] offset:128
	global_load_dwordx4 v[116:119], v7, s[82:83] offset:192
	s_waitcnt vmcnt(36)
	v_cvt_pk_bf16_f32 v120, v8, v9
	v_cvt_pk_bf16_f32 v121, v10, v11
	v_cvt_pk_bf16_f32 v122, v12, v13
	v_cvt_pk_bf16_f32 v123, v14, v15
	v_cvt_pk_bf16_f32 v124, v16, v17
	v_cvt_pk_bf16_f32 v125, v18, v19
	v_cvt_pk_bf16_f32 v126, v20, v21
	v_cvt_pk_bf16_f32 v127, v22, v23
	s_add_i32 s37, s39, 0
	s_lshl_b32 s38, s37, 13
	s_add_u32 s40, s44, s38
	s_addc_u32 s41, s45, 0
	global_store_dwordx2 v6, v[120:121], s[40:41]
	global_store_dwordx2 v6, v[122:123], s[40:41] offset:512
	global_store_dwordx2 v6, v[124:125], s[40:41] offset:1024
	global_store_dwordx2 v6, v[126:127], s[40:41] offset:1536
	v_lshlrev_b32_e32 v128, 16, v24
	v_and_b32_e32 v129, 0xffff0000, v24
	v_lshlrev_b32_e32 v130, 16, v25
	v_and_b32_e32 v131, 0xffff0000, v25
	v_fma_f32 v8, v56, v8, v128
	v_fma_f32 v9, v57, v9, v129
	v_fma_f32 v10, v58, v10, v130
	v_fma_f32 v11, v59, v11, v131
	v_lshlrev_b32_e32 v128, 16, v26
	v_and_b32_e32 v129, 0xffff0000, v26
	v_lshlrev_b32_e32 v130, 16, v27
	v_and_b32_e32 v131, 0xffff0000, v27
	v_fma_f32 v12, v60, v12, v128
	v_fma_f32 v13, v61, v13, v129
	v_fma_f32 v14, v62, v14, v130
	v_fma_f32 v15, v63, v15, v131
	v_lshlrev_b32_e32 v128, 16, v28
	v_and_b32_e32 v129, 0xffff0000, v28
	v_lshlrev_b32_e32 v130, 16, v29
	v_and_b32_e32 v131, 0xffff0000, v29
	v_fma_f32 v16, v64, v16, v128
	v_fma_f32 v17, v65, v17, v129
	v_fma_f32 v18, v66, v18, v130
	v_fma_f32 v19, v67, v19, v131
	v_lshlrev_b32_e32 v128, 16, v30
	v_and_b32_e32 v129, 0xffff0000, v30
	v_lshlrev_b32_e32 v130, 16, v31
	v_and_b32_e32 v131, 0xffff0000, v31
	v_fma_f32 v20, v68, v20, v128
	v_fma_f32 v21, v69, v21, v129
	v_fma_f32 v22, v70, v22, v130
	v_fma_f32 v23, v71, v23, v131
	s_add_i32 s37, s39, 4
	s_min_u32 s37, s37, 0x7f
	s_lshl_b32 s38, s37, 13
	s_add_u32 s82, s44, s38
	s_addc_u32 s83, s45, 0
	global_load_dwordx2 v[24:25], v6, s[82:83]
	global_load_dwordx2 v[26:27], v6, s[82:83] offset:512
	global_load_dwordx2 v[28:29], v6, s[82:83] offset:1024
	global_load_dwordx2 v[30:31], v6, s[82:83] offset:1536
	s_lshl_b32 s38, s37, 8
	s_add_u32 s82, s46, s38
	s_addc_u32 s83, s47, 0
	global_load_dwordx4 v[56:59], v7, s[82:83]
	global_load_dwordx4 v[60:63], v7, s[82:83] offset:64
	global_load_dwordx4 v[64:67], v7, s[82:83] offset:128
	global_load_dwordx4 v[68:71], v7, s[82:83] offset:192
	s_waitcnt vmcnt(36)
; __device__ __forceinline__ float bf_lo(unsigned u) { return __uint_as_float(u << 16); }
; __device__ __forceinline__ float bf_hi(unsigned u) { return __uint_as_float(u & 0xffff0000u); }
; __device__ __forceinline__ unsigned pk2(float lo, float hi) { return pg8::cvt_pk_bf16(lo, hi); }
; #define SCAN_LOAD_D(slot, cc) { const int c_ = (cc) < NCH ? (cc) : NCH - 1; const bf16_t* bcn = bc0 + (size_t)c_ * 4096; \
;             _Pragma("unroll") for (int t = 0; t < 4; ++t) { cb[slot][t] = *(const u32x2*)(bcn + 256 * t); cm[slot][t] = mixer == 2 ? *(const f32x4*)(mv0 + (size_t)c_ * 64 + 16 * t) : (f32x4){g64, g64, g64, g64}; } }
; __device__ __forceinline__ void scan_phase(const Ctx& X, int wave, int lane) {
;     ...
;         for (int c0 = 0; c0 < NCH; c0 += 4) {
; #pragma unroll
;             for (int k = 0; k < 4; ++k) {
;                 const int c = c0 + k;
;                 SCAN_LOAD_D((k + 3) & 3, c + 3)
;                 bf16_t* bcc = bc0 + (size_t)c * 4096;
; #pragma unroll
;                 for (int t = 0; t < 4; ++t) { u32x2 sp; sp.x = pk2(S[t][0], S[t][1]); sp.y = pk2(S[t][2], S[t][3]);
;                     asm volatile("" : "+v"(sp.x) : "v"(cb[k][t].x));
;                     *(u32x2*)(bcc + 256 * t) = sp;
;                     S[t][0] = cm[k][t].x * S[t][0] + bf_lo(cb[k][t].x); S[t][1] = cm[k][t].y * S[t][1] + bf_hi(cb[k][t].x);
;                     S[t][2] = cm[k][t].z * S[t][2] + bf_lo(cb[k][t].y); S[t][3] = cm[k][t].w * S[t][3] + bf_hi(cb[k][t].y); }
;             }
	v_cvt_pk_bf16_f32 v120, v8, v9
	v_cvt_pk_bf16_f32 v121, v10, v11
	v_cvt_pk_bf16_f32 v122, v12, v13
	v_cvt_pk_bf16_f32 v123, v14, v15
	v_cvt_pk_bf16_f32 v124, v16, v17
	v_cvt_pk_bf16_f32 v125, v18, v19
	v_cvt_pk_bf16_f32 v126, v20, v21
	v_cvt_pk_bf16_f32 v127, v22, v23
	s_add_i32 s37, s39, 1
	s_lshl_b32 s38, s37, 13
	s_add_u32 s40, s44, s38
	s_addc_u32 s41, s45, 0
	global_store_dwordx2 v6, v[120:121], s[40:41]
	global_store_dwordx2 v6, v[122:123], s[40:41] offset:512
	global_store_dwordx2 v6, v[124:125], s[40:41] offset:1024
	global_store_dwordx2 v6, v[126:127], s[40:41] offset:1536
	v_lshlrev_b32_e32 v128, 16, v32
	v_and_b32_e32 v129, 0xffff0000, v32
	v_lshlrev_b32_e32 v130, 16, v33
	v_and_b32_e32 v131, 0xffff0000, v33
	v_fma_f32 v8, v72, v8, v128
	v_fma_f32 v9, v73, v9, v129
	v_fma_f32 v10, v74, v10, v130
	v_fma_f32 v11, v75, v11, v131
	v_lshlrev_b32_e32 v128, 16, v34
	v_and_b32_e32 v129, 0xffff0000, v34
	v_lshlrev_b32_e32 v130, 16, v35
	v_and_b32_e32 v131, 0xffff0000, v35
	v_fma_f32 v12, v76, v12, v128
	v_fma_f32 v13, v77, v13, v129
	v_fma_f32 v14, v78, v14, v130
	v_fma_f32 v15, v79, v15, v131
	v_lshlrev_b32_e32 v128, 16, v36
	v_and_b32_e32 v129, 0xffff0000, v36
	v_lshlrev_b32_e32 v130, 16, v37
	v_and_b32_e32 v131, 0xffff0000, v37
	v_fma_f32 v16, v80, v16, v128
	v_fma_f32 v17, v81, v17, v129
	v_fma_f32 v18, v82, v18, v130
	v_fma_f32 v19, v83, v19, v131
	v_lshlrev_b32_e32 v128, 16, v38
	v_and_b32_e32 v129, 0xffff0000, v38
	v_lshlrev_b32_e32 v130, 16, v39
	v_and_b32_e32 v131, 0xffff0000, v39
	v_fma_f32 v20, v84, v20, v128
	v_fma_f32 v21, v85, v21, v129
	v_fma_f32 v22, v86, v22, v130
	v_fma_f32 v23, v87, v23, v131
	s_add_i32 s37, s39, 5
	s_min_u32 s37, s37, 0x7f
	s_lshl_b32 s38, s37, 13
	s_add_u32 s82, s44, s38
	s_addc_u32 s83, s45, 0
	global_load_dwordx2 v[32:33], v6, s[82:83]
	global_load_dwordx2 v[34:35], v6, s[82:83] offset:512
	global_load_dwordx2 v[36:37], v6, s[82:83] offset:1024
	global_load_dwordx2 v[38:39], v6, s[82:83] offset:1536
	s_lshl_b32 s38, s37, 8
	s_add_u32 s82, s46, s38
	s_addc_u32 s83, s47, 0
	global_load_dwordx4 v[72:75], v7, s[82:83]
	global_load_dwordx4 v[76:79], v7, s[82:83] offset:64
	global_load_dwordx4 v[80:83], v7, s[82:83] offset:128
	global_load_dwordx4 v[84:87], v7, s[82:83] offset:192
	s_waitcnt vmcnt(36)
	v_cvt_pk_bf16_f32 v120, v8, v9
	v_cvt_pk_bf16_f32 v121, v10, v11
	v_cvt_pk_bf16_f32 v122, v12, v13
	v_cvt_pk_bf16_f32 v123, v14, v15
	v_cvt_pk_bf16_f32 v124, v16, v17
	v_cvt_pk_bf16_f32 v125, v18, v19
	v_cvt_pk_bf16_f32 v126, v20, v21
	v_cvt_pk_bf16_f32 v127, v22, v23
	s_add_i32 s37, s39, 2
	s_lshl_b32 s38, s37, 13
	s_add_u32 s40, s44, s38
	s_addc_u32 s41, s45, 0
	global_store_dwordx2 v6, v[120:121], s[40:41]
	global_store_dwordx2 v6, v[122:123], s[40:41] offset:512
	global_store_dwordx2 v6, v[124:125], s[40:41] offset:1024
	global_store_dwordx2 v6, v[126:127], s[40:41] offset:1536
	v_lshlrev_b32_e32 v128, 16, v40
	v_and_b32_e32 v129, 0xffff0000, v40
	v_lshlrev_b32_e32 v130, 16, v41
	v_and_b32_e32 v131, 0xffff0000, v41
	v_fma_f32 v8, v88, v8, v128
	v_fma_f32 v9, v89, v9, v129
	v_fma_f32 v10, v90, v10, v130
	v_fma_f32 v11, v91, v11, v131
	v_lshlrev_b32_e32 v128, 16, v42
	v_and_b32_e32 v129, 0xffff0000, v42
	v_lshlrev_b32_e32 v130, 16, v43
	v_and_b32_e32 v131, 0xffff0000, v43
	v_fma_f32 v12, v92, v12, v128
	v_fma_f32 v13, v93, v13, v129
	v_fma_f32 v14, v94, v14, v130
	v_fma_f32 v15, v95, v15, v131
	v_lshlrev_b32_e32 v128, 16, v44
	v_and_b32_e32 v129, 0xffff0000, v44
	v_lshlrev_b32_e32 v130, 16, v45
	v_and_b32_e32 v131, 0xffff0000, v45
	v_fma_f32 v16, v96, v16, v128
	v_fma_f32 v17, v97, v17, v129
	v_fma_f32 v18, v98, v18, v130
	v_fma_f32 v19, v99, v19, v131
	v_lshlrev_b32_e32 v128, 16, v46
	v_and_b32_e32 v129, 0xffff0000, v46
	v_lshlrev_b32_e32 v130, 16, v47
	v_and_b32_e32 v131, 0xffff0000, v47
	v_fma_f32 v20, v100, v20, v128
	v_fma_f32 v21, v101, v21, v129
	v_fma_f32 v22, v102, v22, v130
	v_fma_f32 v23, v103, v23, v131
	s_add_i32 s37, s39, 6
	s_min_u32 s37, s37, 0x7f
	s_lshl_b32 s38, s37, 13
	s_add_u32 s82, s44, s38
	s_addc_u32 s83, s45, 0
	global_load_dwordx2 v[40:41], v6, s[82:83]
	global_load_dwordx2 v[42:43], v6, s[82:83] offset:512
	global_load_dwordx2 v[44:45], v6, s[82:83] offset:1024
	global_load_dwordx2 v[46:47], v6, s[82:83] offset:1536
	s_lshl_b32 s38, s37, 8
	s_add_u32 s82, s46, s38
	s_addc_u32 s83, s47, 0
	global_load_dwordx4 v[88:91], v7, s[82:83]
	global_load_dwordx4 v[92:95], v7, s[82:83] offset:64
	global_load_dwordx4 v[96:99], v7, s[82:83] offset:128
	global_load_dwordx4 v[100:103], v7, s[82:83] offset:192
	s_waitcnt vmcnt(36)
	v_cvt_pk_bf16_f32 v120, v8, v9
	v_cvt_pk_bf16_f32 v121, v10, v11
	v_cvt_pk_bf16_f32 v122, v12, v13
	v_cvt_pk_bf16_f32 v123, v14, v15
	v_cvt_pk_bf16_f32 v124, v16, v17
	v_cvt_pk_bf16_f32 v125, v18, v19
	v_cvt_pk_bf16_f32 v126, v20, v21
	v_cvt_pk_bf16_f32 v127, v22, v23
	s_add_i32 s37, s39, 3
	s_lshl_b32 s38, s37, 13
	s_add_u32 s40, s44, s38
	s_addc_u32 s41, s45, 0
	global_store_dwordx2 v6, v[120:121], s[40:41]
	global_store_dwordx2 v6, v[122:123], s[40:41] offset:512
	global_store_dwordx2 v6, v[124:125], s[40:41] offset:1024
	global_store_dwordx2 v6, v[126:127], s[40:41] offset:1536
	v_lshlrev_b32_e32 v128, 16, v48
	v_and_b32_e32 v129, 0xffff0000, v48
	v_lshlrev_b32_e32 v130, 16, v49
	v_and_b32_e32 v131, 0xffff0000, v49
	v_fma_f32 v8, v104, v8, v128
	v_fma_f32 v9, v105, v9, v129
	v_fma_f32 v10, v106, v10, v130
	v_fma_f32 v11, v107, v11, v131
	v_lshlrev_b32_e32 v128, 16, v50
	v_and_b32_e32 v129, 0xffff0000, v50
	v_lshlrev_b32_e32 v130, 16, v51
	v_and_b32_e32 v131, 0xffff0000, v51
	v_fma_f32 v12, v108, v12, v128
	v_fma_f32 v13, v109, v13, v129
	v_fma_f32 v14, v110, v14, v130
	v_fma_f32 v15, v111, v15, v131
	v_lshlrev_b32_e32 v128, 16, v52
	v_and_b32_e32 v129, 0xffff0000, v52
	v_lshlrev_b32_e32 v130, 16, v53
	v_and_b32_e32 v131, 0xffff0000, v53
	v_fma_f32 v16, v112, v16, v128
	v_fma_f32 v17, v113, v17, v129
	v_fma_f32 v18, v114, v18, v130
	v_fma_f32 v19, v115, v19, v131
	v_lshlrev_b32_e32 v128, 16, v54
	v_and_b32_e32 v129, 0xffff0000, v54
	v_lshlrev_b32_e32 v130, 16, v55
	v_and_b32_e32 v131, 0xffff0000, v55
	v_fma_f32 v20, v116, v20, v128
	v_fma_f32 v21, v117, v21, v129
	v_fma_f32 v22, v118, v22, v130
	v_fma_f32 v23, v119, v23, v131
	s_add_i32 s39, s39, 4
	s_cmpk_lt_u32 s39, 0x80
	s_cbranch_scc1 .Lsd2_loop
	s_branch .LBB0_739

; #define LAS __attribute__((address_space(3)))
; template <class Tp> __device__ __forceinline__ LAS Tp* opq(LAS Tp* p) { asm volatile("" : "+v"(p)); return p; }
; __device__ __forceinline__ int unit_id(int mixer, int b, int h, int c) { return ((mixer * 4 + b) * 4 + h) * NCH + c; }
; __device__ __forceinline__ void mixer_out_phase(const Ctx& X, LAS unsigned char* lds, int layer, int tid, int wave, int lane) {
;     constexpr int GP = 264;
;     const bf16_t* proj = WSP(const bf16_t, WS_PROJ);
;     bf16_t* mix = WSP(bf16_t, WS_MIX);
;     for (int u = blockIdx.x; u < 1536; u += gridDim.x) {
;         asm volatile("" : "+v"(lane), "+v"(tid));
;         LAS bf16_t* GT = opq((LAS bf16_t*)lds);
;         const int r = lane & 15, q = lane >> 4, h = wave >> 1, half = wave & 1;
;         const int mixer = u >> 9, rem = u & 511, b = rem >> 7, c = rem & 127;
;         const int uid = unit_id(mixer, b, h, c);
;         const int goff = mixer == 0 ? C_RG : (mixer == 1 ? C_GG : C_HG), moff = mixer == 0 ? 0 : (mixer == 1 ? 512 : 768);
;         const size_t row0 = (size_t)b * T + c * 64;
;         u32x4 gv[4];
.Lgs2_done:
	s_waitcnt vmcnt(0)
	s_branch .Lgs2_pad
	s_nop 0
.Lgs2_pad:
.LBB0_886:
	s_or_b64 exec, exec, s[0:1]
	v_readlane_b32 s0, v253, 56
	v_readlane_b32 s1, v253, 57
	s_andn2_b64 vcc, exec, s[0:1]
	s_waitcnt lgkmcnt(0)
	s_barrier
	s_cbranch_vccnz .LBB0_890
	v_readlane_b32 s0, v254, 61
	v_readlane_b32 s1, v254, 62
	s_lshl_b32 s16, s0, 6
	s_lshl_b32 s0, s0, 8
	s_mov_b32 s1, s17
	s_lshl_b64 s[0:1], s[0:1], 2
	v_readlane_b32 s4, v253, 61
	s_add_u32 s8, s4, s0
	v_readlane_b32 s0, v253, 62
	v_readlane_b32 s44, v253, 38
	s_addc_u32 s9, s0, s1
	s_lshl_b64 s[4:5], s[16:17], 2
	v_mov_b32_e32 v104, v224
	v_mov_b32_e32 v105, v232
	s_mov_b32 s10, s2
	v_readlane_b32 s50, v253, 44
	v_readlane_b32 s51, v253, 45
	v_readlane_b32 s54, v253, 48
	v_readlane_b32 s55, v253, 49
	v_readlane_b32 s19, v253, 1
	v_readlane_b32 s20, v253, 2
	v_readlane_b32 s21, v253, 58
	v_readlane_b32 s22, v253, 59
	v_readlane_b32 s23, v253, 60
	v_readlane_b32 s45, v253, 39
	v_readlane_b32 s46, v253, 40
	v_readlane_b32 s47, v253, 41
	v_readlane_b32 s48, v253, 42
	v_readlane_b32 s49, v253, 43
	v_readlane_b32 s52, v253, 46
	v_readlane_b32 s53, v253, 47
	v_readlane_b32 s56, v253, 50
	v_readlane_b32 s57, v253, 51
	v_readlane_b32 s58, v253, 52
	v_readlane_b32 s59, v253, 53
